# mirror of v11: static s_setprio 1 for waves 0-3 (older half) instead of 4-7 during attention
# speedup vs baseline: 1.0051x; 1.0051x over previous
; #define LAS __attribute__((address_space(3)))
; DI void phase_attn(const bf16_t* Q, const bf16_t* Kb, const bf16_t* Vt, bf16_t* AO, LAS unsigned char* lds, int tid, int wave, int lane, const Grp gr) {
;     for (int k = gr.mi; k < 64; k += gr.GM) {
;         const int pp = gr.grp * 64 + k, bh = pp >> 3, j = pp & 7;
;         attn_block(Q, Kb, Vt, AO, lds, bh, 15 - j, tid, wave, lane);
.LBB0_418:
	s_or_b64 exec, exec, s[0:1]
	s_cmpk_lt_u32 s72, 0x200
	s_cselect_b64 s[2:3], -1, 0
	v_writelane_b32 v253, s2, 32
	s_mov_b64 s[0:1], s[76:77]
	s_mov_b32 s4, s75
	v_mov_b32_e32 v0, 0
	v_mov_b32_e32 v1, 0
	v_writelane_b32 v253, s3, 33
	s_cmpk_gt_u32 s72, 0x1ff
	s_barrier
	s_cbranch_scc1 .LBB0_449
	s_cmp_ge_u32 s75, 4
	s_cbranch_scc1 .Lattn_prio_skip_0
	s_setprio 1

; #define LAS __attribute__((address_space(3)))
; DI void phase_attn(const bf16_t* Q, const bf16_t* Kb, const bf16_t* Vt, bf16_t* AO, LAS unsigned char* lds, int tid, int wave, int lane, const Grp gr) {
;     for (int k = gr.mi; k < 64; k += gr.GM) {
;         const int pp = gr.grp * 64 + k, bh = pp >> 3, j = pp & 7;
;         attn_block(Q, Kb, Vt, AO, lds, bh, 15 - j, tid, wave, lane);
.LBB0_1164:
	s_or_b64 exec, exec, s[0:1]
	v_readlane_b32 s2, v253, 32
	v_readlane_b32 s3, v253, 33
	s_mov_b64 s[0:1], s[76:77]
	s_mov_b32 s4, s75
	v_mov_b32_e32 v0, 0
	v_mov_b32_e32 v1, 0
	s_andn2_b64 vcc, exec, s[2:3]
	s_barrier
	s_cbranch_vccnz .LBB0_1195
	s_cmp_ge_u32 s75, 4
	s_cbranch_scc1 .Lattn_prio_skip_1
	s_setprio 1
